# tile headers: redundant first accumulator zeroing (127 v_mov per tile) moved to the never-taken no-K-loop path
# speedup vs baseline: 1.0032x; 1.0032x over previous
; template <class Epi, class Sched, bool ALIGN_EPI = false, bool SP2 = false>
; __device__ __forceinline__ void gemm_phase(PG8_LAS unsigned char* lds, const Gemm g, const Sched& S, const Epi& E) {
;     ...
;         for (int a = 0; a < 2; ++a)
; #pragma unroll
;             for (int b = 0; b < 2; ++b)
; #pragma unroll
;                 for (int m = 0; m < 4; ++m)
; #pragma unroll
;                     for (int n = 0; n < 2; ++n) acc[a][b][m][n] = (f32x4){0.f, 0.f, 0.f, 0.f};
.Lmy_z0:
	v_mov_b32_e32 v160, v161
	v_mov_b32_e32 v159, v161
	v_mov_b32_e32 v158, v161
	v_mov_b32_e32 v63, v161
	v_mov_b32_e32 v62, v161
	v_mov_b32_e32 v61, v161
	v_mov_b32_e32 v60, v161
	v_mov_b32_e32 v153, v161
	v_mov_b32_e32 v152, v161
	v_mov_b32_e32 v151, v161
	v_mov_b32_e32 v150, v161
	v_mov_b32_e32 v55, v161
	v_mov_b32_e32 v54, v161
	v_mov_b32_e32 v53, v161
	v_mov_b32_e32 v52, v161
	v_mov_b32_e32 v103, v161
	v_mov_b32_e32 v102, v161
	v_mov_b32_e32 v101, v161
	v_mov_b32_e32 v100, v161
	v_mov_b32_e32 v39, v161
	v_mov_b32_e32 v38, v161
	v_mov_b32_e32 v37, v161
	v_mov_b32_e32 v36, v161
	v_mov_b32_e32 v119, v161
	v_mov_b32_e32 v118, v161
	v_mov_b32_e32 v117, v161
	v_mov_b32_e32 v116, v161
	v_mov_b32_e32 v71, v161
	v_mov_b32_e32 v70, v161
	v_mov_b32_e32 v69, v161
	v_mov_b32_e32 v68, v161
	v_mov_b32_e32 v157, v161
	v_mov_b32_e32 v156, v161
	v_mov_b32_e32 v155, v161
	v_mov_b32_e32 v154, v161
	v_mov_b32_e32 v59, v161
	v_mov_b32_e32 v58, v161
	v_mov_b32_e32 v57, v161
	v_mov_b32_e32 v56, v161
	v_mov_b32_e32 v149, v161
	v_mov_b32_e32 v148, v161
	v_mov_b32_e32 v147, v161
	v_mov_b32_e32 v146, v161
	v_mov_b32_e32 v51, v161
	v_mov_b32_e32 v50, v161
	v_mov_b32_e32 v49, v161
	v_mov_b32_e32 v48, v161
	v_mov_b32_e32 v99, v161
	v_mov_b32_e32 v98, v161
	v_mov_b32_e32 v97, v161
	v_mov_b32_e32 v96, v161
	v_mov_b32_e32 v35, v161
	v_mov_b32_e32 v34, v161
	v_mov_b32_e32 v33, v161
	v_mov_b32_e32 v32, v161
	v_mov_b32_e32 v115, v161
	v_mov_b32_e32 v114, v161
	v_mov_b32_e32 v113, v161
	v_mov_b32_e32 v112, v161
	v_mov_b32_e32 v67, v161
	v_mov_b32_e32 v66, v161
	v_mov_b32_e32 v65, v161
	v_mov_b32_e32 v64, v161
	v_mov_b32_e32 v95, v161
	v_mov_b32_e32 v94, v161
	v_mov_b32_e32 v93, v161
	v_mov_b32_e32 v92, v161
	v_mov_b32_e32 v31, v161
	v_mov_b32_e32 v30, v161
	v_mov_b32_e32 v29, v161
	v_mov_b32_e32 v28, v161
	v_mov_b32_e32 v87, v161
	v_mov_b32_e32 v86, v161
	v_mov_b32_e32 v85, v161
	v_mov_b32_e32 v84, v161
	v_mov_b32_e32 v23, v161
	v_mov_b32_e32 v22, v161
	v_mov_b32_e32 v21, v161
	v_mov_b32_e32 v20, v161
	v_mov_b32_e32 v79, v161
	v_mov_b32_e32 v78, v161
	v_mov_b32_e32 v77, v161
	v_mov_b32_e32 v76, v161
	v_mov_b32_e32 v15, v161
	v_mov_b32_e32 v14, v161
	v_mov_b32_e32 v13, v161
	v_mov_b32_e32 v12, v161
	v_mov_b32_e32 v111, v161
	v_mov_b32_e32 v110, v161
	v_mov_b32_e32 v109, v161
	v_mov_b32_e32 v108, v161
	v_mov_b32_e32 v47, v161
	v_mov_b32_e32 v46, v161
	v_mov_b32_e32 v45, v161
	v_mov_b32_e32 v44, v161
	v_mov_b32_e32 v91, v161
	v_mov_b32_e32 v90, v161
	v_mov_b32_e32 v89, v161
	v_mov_b32_e32 v88, v161
	v_mov_b32_e32 v27, v161
	v_mov_b32_e32 v26, v161
	v_mov_b32_e32 v25, v161
	v_mov_b32_e32 v24, v161
	v_mov_b32_e32 v83, v161
	v_mov_b32_e32 v82, v161
	v_mov_b32_e32 v81, v161
	v_mov_b32_e32 v80, v161
	v_mov_b32_e32 v19, v161
	v_mov_b32_e32 v18, v161
	v_mov_b32_e32 v17, v161
	v_mov_b32_e32 v16, v161
	v_mov_b32_e32 v75, v161
	v_mov_b32_e32 v74, v161
	v_mov_b32_e32 v73, v161
	v_mov_b32_e32 v72, v161
	v_mov_b32_e32 v11, v161
	v_mov_b32_e32 v10, v161
	v_mov_b32_e32 v9, v161
	v_mov_b32_e32 v8, v161
	v_mov_b32_e32 v107, v161
	v_mov_b32_e32 v106, v161
	v_mov_b32_e32 v105, v161
	v_mov_b32_e32 v104, v161
	v_mov_b32_e32 v43, v161
	v_mov_b32_e32 v42, v161
	v_mov_b32_e32 v41, v161
	v_mov_b32_e32 v40, v161
	s_branch .LBB0_366

; template <class Epi, class Sched, bool ALIGN_EPI = false, bool SP2 = false>
; __device__ __forceinline__ void gemm_phase(PG8_LAS unsigned char* lds, const Gemm g, const Sched& S, const Epi& E) {
;     ...
;         for (int a = 0; a < 2; ++a)
; #pragma unroll
;             for (int b = 0; b < 2; ++b)
; #pragma unroll
;                 for (int m = 0; m < 4; ++m)
; #pragma unroll
;                     for (int n = 0; n < 2; ++n) acc[a][b][m][n] = (f32x4){0.f, 0.f, 0.f, 0.f};
.LBB0_363:
	v_readlane_b32 s38, v252, 59
	v_mov_b32_e32 v161, 0
	v_readlane_b32 s39, v252, 60
	s_andn2_b64 vcc, exec, s[38:39]
	s_waitcnt vmcnt(0)
	s_cbranch_vccnz .Lmy_z0
	s_add_u32 s0, s0, 0x80
	s_addc_u32 s1, s1, 0
	s_add_u32 s72, s86, 0x100
	v_mov_b32_e32 v40, 0
	s_addc_u32 s73, s87, 0
	s_mov_b32 s86, 0
	v_mov_b32_e32 v41, v40
	v_mov_b32_e32 v42, v40
	v_mov_b32_e32 v43, v40
	v_mov_b32_e32 v104, v40
	v_mov_b32_e32 v105, v40
	v_mov_b32_e32 v106, v40
	v_mov_b32_e32 v107, v40
	v_mov_b32_e32 v8, v40
	v_mov_b32_e32 v9, v40
	v_mov_b32_e32 v10, v40
	v_mov_b32_e32 v11, v40
	v_mov_b32_e32 v72, v40
	v_mov_b32_e32 v73, v40
	v_mov_b32_e32 v74, v40
	v_mov_b32_e32 v75, v40
	v_mov_b32_e32 v16, v40
	v_mov_b32_e32 v17, v40
	v_mov_b32_e32 v18, v40
	v_mov_b32_e32 v19, v40
	v_mov_b32_e32 v80, v40
	v_mov_b32_e32 v81, v40
	v_mov_b32_e32 v82, v40
	v_mov_b32_e32 v83, v40
	v_mov_b32_e32 v24, v40
	v_mov_b32_e32 v25, v40
	v_mov_b32_e32 v26, v40
	v_mov_b32_e32 v27, v40
	v_mov_b32_e32 v88, v40
	v_mov_b32_e32 v89, v40
	v_mov_b32_e32 v90, v40
	v_mov_b32_e32 v91, v40
	v_mov_b32_e32 v44, v40
	v_mov_b32_e32 v45, v40
	v_mov_b32_e32 v46, v40
	v_mov_b32_e32 v47, v40
	v_mov_b32_e32 v108, v40
	v_mov_b32_e32 v109, v40
	v_mov_b32_e32 v110, v40
	v_mov_b32_e32 v111, v40
	v_mov_b32_e32 v12, v40
	v_mov_b32_e32 v13, v40
	v_mov_b32_e32 v14, v40
	v_mov_b32_e32 v15, v40
	v_mov_b32_e32 v76, v40
	v_mov_b32_e32 v77, v40
	v_mov_b32_e32 v78, v40
	v_mov_b32_e32 v79, v40
	v_mov_b32_e32 v20, v40
	v_mov_b32_e32 v21, v40
	v_mov_b32_e32 v22, v40
	v_mov_b32_e32 v23, v40
	v_mov_b32_e32 v84, v40
	v_mov_b32_e32 v85, v40
	v_mov_b32_e32 v86, v40
	v_mov_b32_e32 v87, v40
	v_mov_b32_e32 v28, v40
	v_mov_b32_e32 v29, v40
	v_mov_b32_e32 v30, v40
	v_mov_b32_e32 v31, v40
	v_mov_b32_e32 v92, v40
	v_mov_b32_e32 v93, v40
	v_mov_b32_e32 v94, v40
	v_mov_b32_e32 v95, v40
	v_mov_b32_e32 v64, v40
	v_mov_b32_e32 v65, v40
	v_mov_b32_e32 v66, v40
	v_mov_b32_e32 v67, v40
	v_mov_b32_e32 v112, v40
	v_mov_b32_e32 v113, v40
	v_mov_b32_e32 v114, v40
	v_mov_b32_e32 v115, v40
	v_mov_b32_e32 v32, v40
	v_mov_b32_e32 v33, v40
	v_mov_b32_e32 v34, v40
	v_mov_b32_e32 v35, v40
	v_mov_b32_e32 v96, v40
	v_mov_b32_e32 v97, v40
	v_mov_b32_e32 v98, v40
	v_mov_b32_e32 v99, v40
	v_mov_b32_e32 v48, v40
	v_mov_b32_e32 v49, v40
	v_mov_b32_e32 v50, v40
	v_mov_b32_e32 v51, v40
	v_mov_b32_e32 v146, v40
	v_mov_b32_e32 v147, v40
	v_mov_b32_e32 v148, v40
	v_mov_b32_e32 v149, v40
	v_mov_b32_e32 v56, v40
	v_mov_b32_e32 v57, v40
	v_mov_b32_e32 v58, v40
	v_mov_b32_e32 v59, v40
	v_mov_b32_e32 v154, v40
	v_mov_b32_e32 v155, v40
	v_mov_b32_e32 v156, v40
	v_mov_b32_e32 v157, v40
	v_mov_b32_e32 v68, v40
	v_mov_b32_e32 v69, v40
	v_mov_b32_e32 v70, v40
	v_mov_b32_e32 v71, v40
	v_mov_b32_e32 v116, v40
	v_mov_b32_e32 v117, v40
	v_mov_b32_e32 v118, v40
	v_mov_b32_e32 v119, v40
	v_mov_b32_e32 v36, v40
	v_mov_b32_e32 v37, v40
	v_mov_b32_e32 v38, v40
	v_mov_b32_e32 v39, v40
	v_mov_b32_e32 v100, v40
	v_mov_b32_e32 v101, v40
	v_mov_b32_e32 v102, v40
	v_mov_b32_e32 v103, v40
	v_mov_b32_e32 v52, v40
	v_mov_b32_e32 v53, v40
	v_mov_b32_e32 v54, v40
	v_mov_b32_e32 v55, v40
	v_mov_b32_e32 v150, v40
	v_mov_b32_e32 v151, v40
	v_mov_b32_e32 v152, v40
	v_mov_b32_e32 v153, v40
	v_mov_b32_e32 v60, v40
	v_mov_b32_e32 v61, v40
	v_mov_b32_e32 v62, v40
	v_mov_b32_e32 v63, v40
	v_mov_b32_e32 v158, v40
	v_mov_b32_e32 v159, v40
	v_mov_b32_e32 v160, v40
	v_mov_b32_e32 v161, v40

; template <class Epi, class Sched, bool ALIGN_EPI = false, bool SP2 = false>
; __device__ __forceinline__ void gemm_phase(PG8_LAS unsigned char* lds, const Gemm g, const Sched& S, const Epi& E) {
;     ...
;         for (int a = 0; a < 2; ++a)
; #pragma unroll
;             for (int b = 0; b < 2; ++b)
; #pragma unroll
;                 for (int m = 0; m < 4; ++m)
; #pragma unroll
;                     for (int n = 0; n < 2; ++n) acc[a][b][m][n] = (f32x4){0.f, 0.f, 0.f, 0.f};
.Lmy_z2:
	v_mov_b32_e32 v134, v135
	v_mov_b32_e32 v133, v135
	v_mov_b32_e32 v132, v135
	v_mov_b32_e32 v131, v135
	v_mov_b32_e32 v130, v135
	v_mov_b32_e32 v129, v135
	v_mov_b32_e32 v128, v135
	v_mov_b32_e32 v119, v135
	v_mov_b32_e32 v118, v135
	v_mov_b32_e32 v117, v135
	v_mov_b32_e32 v116, v135
	v_mov_b32_e32 v115, v135
	v_mov_b32_e32 v114, v135
	v_mov_b32_e32 v113, v135
	v_mov_b32_e32 v112, v135
	v_mov_b32_e32 v103, v135
	v_mov_b32_e32 v102, v135
	v_mov_b32_e32 v101, v135
	v_mov_b32_e32 v100, v135
	v_mov_b32_e32 v99, v135
	v_mov_b32_e32 v98, v135
	v_mov_b32_e32 v97, v135
	v_mov_b32_e32 v96, v135
	v_mov_b32_e32 v87, v135
	v_mov_b32_e32 v86, v135
	v_mov_b32_e32 v85, v135
	v_mov_b32_e32 v84, v135
	v_mov_b32_e32 v83, v135
	v_mov_b32_e32 v82, v135
	v_mov_b32_e32 v81, v135
	v_mov_b32_e32 v80, v135
	v_mov_b32_e32 v127, v135
	v_mov_b32_e32 v126, v135
	v_mov_b32_e32 v125, v135
	v_mov_b32_e32 v124, v135
	v_mov_b32_e32 v123, v135
	v_mov_b32_e32 v122, v135
	v_mov_b32_e32 v121, v135
	v_mov_b32_e32 v120, v135
	v_mov_b32_e32 v111, v135
	v_mov_b32_e32 v110, v135
	v_mov_b32_e32 v109, v135
	v_mov_b32_e32 v108, v135
	v_mov_b32_e32 v107, v135
	v_mov_b32_e32 v106, v135
	v_mov_b32_e32 v105, v135
	v_mov_b32_e32 v104, v135
	v_mov_b32_e32 v95, v135
	v_mov_b32_e32 v94, v135
	v_mov_b32_e32 v93, v135
	v_mov_b32_e32 v92, v135
	v_mov_b32_e32 v91, v135
	v_mov_b32_e32 v90, v135
	v_mov_b32_e32 v89, v135
	v_mov_b32_e32 v88, v135
	v_mov_b32_e32 v79, v135
	v_mov_b32_e32 v78, v135
	v_mov_b32_e32 v77, v135
	v_mov_b32_e32 v76, v135
	v_mov_b32_e32 v75, v135
	v_mov_b32_e32 v74, v135
	v_mov_b32_e32 v73, v135
	v_mov_b32_e32 v72, v135
	v_mov_b32_e32 v71, v135
	v_mov_b32_e32 v70, v135
	v_mov_b32_e32 v69, v135
	v_mov_b32_e32 v68, v135
	v_mov_b32_e32 v67, v135
	v_mov_b32_e32 v66, v135
	v_mov_b32_e32 v65, v135
	v_mov_b32_e32 v64, v135
	v_mov_b32_e32 v55, v135
	v_mov_b32_e32 v54, v135
	v_mov_b32_e32 v53, v135
	v_mov_b32_e32 v52, v135
	v_mov_b32_e32 v51, v135
	v_mov_b32_e32 v50, v135
	v_mov_b32_e32 v49, v135
	v_mov_b32_e32 v48, v135
	v_mov_b32_e32 v39, v135
	v_mov_b32_e32 v38, v135
	v_mov_b32_e32 v37, v135
	v_mov_b32_e32 v36, v135
	v_mov_b32_e32 v35, v135
	v_mov_b32_e32 v34, v135
	v_mov_b32_e32 v33, v135
	v_mov_b32_e32 v32, v135
	v_mov_b32_e32 v23, v135
	v_mov_b32_e32 v22, v135
	v_mov_b32_e32 v21, v135
	v_mov_b32_e32 v20, v135
	v_mov_b32_e32 v19, v135
	v_mov_b32_e32 v18, v135
	v_mov_b32_e32 v17, v135
	v_mov_b32_e32 v16, v135
	v_mov_b32_e32 v63, v135
	v_mov_b32_e32 v62, v135
	v_mov_b32_e32 v61, v135
	v_mov_b32_e32 v60, v135
	v_mov_b32_e32 v59, v135
	v_mov_b32_e32 v58, v135
	v_mov_b32_e32 v57, v135
	v_mov_b32_e32 v56, v135
	v_mov_b32_e32 v47, v135
	v_mov_b32_e32 v46, v135
	v_mov_b32_e32 v45, v135
	v_mov_b32_e32 v44, v135
	v_mov_b32_e32 v43, v135
	v_mov_b32_e32 v42, v135
	v_mov_b32_e32 v41, v135
	v_mov_b32_e32 v40, v135
	v_mov_b32_e32 v31, v135
	v_mov_b32_e32 v30, v135
	v_mov_b32_e32 v29, v135
	v_mov_b32_e32 v28, v135
	v_mov_b32_e32 v27, v135
	v_mov_b32_e32 v26, v135
	v_mov_b32_e32 v25, v135
	v_mov_b32_e32 v24, v135
	v_mov_b32_e32 v15, v135
	v_mov_b32_e32 v14, v135
	v_mov_b32_e32 v13, v135
	v_mov_b32_e32 v12, v135
	v_mov_b32_e32 v11, v135
	v_mov_b32_e32 v10, v135
	v_mov_b32_e32 v9, v135
	v_mov_b32_e32 v8, v135
	s_branch .LBB0_469

; template <class Epi, class Sched, bool ALIGN_EPI = false, bool SP2 = false>
; __device__ __forceinline__ void gemm_phase(PG8_LAS unsigned char* lds, const Gemm g, const Sched& S, const Epi& E) {
;     ...
;         for (int a = 0; a < 2; ++a)
; #pragma unroll
;             for (int b = 0; b < 2; ++b)
; #pragma unroll
;                 for (int m = 0; m < 4; ++m)
; #pragma unroll
;                     for (int n = 0; n < 2; ++n) acc[a][b][m][n] = (f32x4){0.f, 0.f, 0.f, 0.f};
.LBB0_466:
	v_readlane_b32 s40, v252, 59
	v_mov_b32_e32 v135, 0
	v_readlane_b32 s41, v252, 60
	s_andn2_b64 vcc, exec, s[40:41]
	s_waitcnt vmcnt(0)
	s_cbranch_vccnz .Lmy_z2
	s_add_u32 s0, s0, 0x80
	s_addc_u32 s1, s1, 0
	s_add_u32 s40, s38, 0x100
	v_mov_b32_e32 v8, 0
	s_addc_u32 s41, s39, 0
	s_mov_b32 s38, 0
	v_mov_b32_e32 v9, v8
	v_mov_b32_e32 v10, v8
	v_mov_b32_e32 v11, v8
	v_mov_b32_e32 v12, v8
	v_mov_b32_e32 v13, v8
	v_mov_b32_e32 v14, v8
	v_mov_b32_e32 v15, v8
	v_mov_b32_e32 v24, v8
	v_mov_b32_e32 v25, v8
	v_mov_b32_e32 v26, v8
	v_mov_b32_e32 v27, v8
	v_mov_b32_e32 v28, v8
	v_mov_b32_e32 v29, v8
	v_mov_b32_e32 v30, v8
	v_mov_b32_e32 v31, v8
	v_mov_b32_e32 v40, v8
	v_mov_b32_e32 v41, v8
	v_mov_b32_e32 v42, v8
	v_mov_b32_e32 v43, v8
	v_mov_b32_e32 v44, v8
	v_mov_b32_e32 v45, v8
	v_mov_b32_e32 v46, v8
	v_mov_b32_e32 v47, v8
	v_mov_b32_e32 v56, v8
	v_mov_b32_e32 v57, v8
	v_mov_b32_e32 v58, v8
	v_mov_b32_e32 v59, v8
	v_mov_b32_e32 v60, v8
	v_mov_b32_e32 v61, v8
	v_mov_b32_e32 v62, v8
	v_mov_b32_e32 v63, v8
	v_mov_b32_e32 v16, v8
	v_mov_b32_e32 v17, v8
	v_mov_b32_e32 v18, v8
	v_mov_b32_e32 v19, v8
	v_mov_b32_e32 v20, v8
	v_mov_b32_e32 v21, v8
	v_mov_b32_e32 v22, v8
	v_mov_b32_e32 v23, v8
	v_mov_b32_e32 v32, v8
	v_mov_b32_e32 v33, v8
	v_mov_b32_e32 v34, v8
	v_mov_b32_e32 v35, v8
	v_mov_b32_e32 v36, v8
	v_mov_b32_e32 v37, v8
	v_mov_b32_e32 v38, v8
	v_mov_b32_e32 v39, v8
	v_mov_b32_e32 v48, v8
	v_mov_b32_e32 v49, v8
	v_mov_b32_e32 v50, v8
	v_mov_b32_e32 v51, v8
	v_mov_b32_e32 v52, v8
	v_mov_b32_e32 v53, v8
	v_mov_b32_e32 v54, v8
	v_mov_b32_e32 v55, v8
	v_mov_b32_e32 v64, v8
	v_mov_b32_e32 v65, v8
	v_mov_b32_e32 v66, v8
	v_mov_b32_e32 v67, v8
	v_mov_b32_e32 v68, v8
	v_mov_b32_e32 v69, v8
	v_mov_b32_e32 v70, v8
	v_mov_b32_e32 v71, v8
	v_mov_b32_e32 v72, v8
	v_mov_b32_e32 v73, v8
	v_mov_b32_e32 v74, v8
	v_mov_b32_e32 v75, v8
	v_mov_b32_e32 v76, v8
	v_mov_b32_e32 v77, v8
	v_mov_b32_e32 v78, v8
	v_mov_b32_e32 v79, v8
	v_mov_b32_e32 v88, v8
	v_mov_b32_e32 v89, v8
	v_mov_b32_e32 v90, v8
	v_mov_b32_e32 v91, v8
	v_mov_b32_e32 v92, v8
	v_mov_b32_e32 v93, v8
	v_mov_b32_e32 v94, v8
	v_mov_b32_e32 v95, v8
	v_mov_b32_e32 v104, v8
	v_mov_b32_e32 v105, v8
	v_mov_b32_e32 v106, v8
	v_mov_b32_e32 v107, v8
	v_mov_b32_e32 v108, v8
	v_mov_b32_e32 v109, v8
	v_mov_b32_e32 v110, v8
	v_mov_b32_e32 v111, v8
	v_mov_b32_e32 v120, v8
	v_mov_b32_e32 v121, v8
	v_mov_b32_e32 v122, v8
	v_mov_b32_e32 v123, v8
	v_mov_b32_e32 v124, v8
	v_mov_b32_e32 v125, v8
	v_mov_b32_e32 v126, v8
	v_mov_b32_e32 v127, v8
	v_mov_b32_e32 v80, v8
	v_mov_b32_e32 v81, v8
	v_mov_b32_e32 v82, v8
	v_mov_b32_e32 v83, v8
	v_mov_b32_e32 v84, v8
	v_mov_b32_e32 v85, v8
	v_mov_b32_e32 v86, v8
	v_mov_b32_e32 v87, v8
	v_mov_b32_e32 v96, v8
	v_mov_b32_e32 v97, v8
	v_mov_b32_e32 v98, v8
	v_mov_b32_e32 v99, v8
	v_mov_b32_e32 v100, v8
	v_mov_b32_e32 v101, v8
	v_mov_b32_e32 v102, v8
	v_mov_b32_e32 v103, v8
	v_mov_b32_e32 v112, v8
	v_mov_b32_e32 v113, v8
	v_mov_b32_e32 v114, v8
	v_mov_b32_e32 v115, v8
	v_mov_b32_e32 v116, v8
	v_mov_b32_e32 v117, v8
	v_mov_b32_e32 v118, v8
	v_mov_b32_e32 v119, v8
	v_mov_b32_e32 v128, v8
	v_mov_b32_e32 v129, v8
	v_mov_b32_e32 v130, v8
	v_mov_b32_e32 v131, v8
	v_mov_b32_e32 v132, v8
	v_mov_b32_e32 v133, v8
	v_mov_b32_e32 v134, v8
	v_mov_b32_e32 v135, v8

; template <class Epi, class Sched, bool ALIGN_EPI = false, bool SP2 = false>
; __device__ __forceinline__ void gemm_phase(PG8_LAS unsigned char* lds, const Gemm g, const Sched& S, const Epi& E) {
;     ...
;         for (int a = 0; a < 2; ++a)
; #pragma unroll
;             for (int b = 0; b < 2; ++b)
; #pragma unroll
;                 for (int m = 0; m < 4; ++m)
; #pragma unroll
;                     for (int n = 0; n < 2; ++n) acc[a][b][m][n] = (f32x4){0.f, 0.f, 0.f, 0.f};
.LBB0_499:
	v_readlane_b32 s4, v252, 59
	v_mov_b32_e32 v135, 0
	v_readlane_b32 s5, v252, 60
	s_andn2_b64 vcc, exec, s[4:5]
	s_waitcnt vmcnt(0)
	s_cbranch_vccnz .Lmy_z1
	s_add_u32 s0, s0, 0x80
	s_addc_u32 s1, s1, 0
	s_add_u32 s42, s42, 0x100
	v_mov_b32_e32 v8, 0
	s_addc_u32 s43, s43, 0
	s_mov_b32 s4, 0
	v_mov_b32_e32 v9, v8
	v_mov_b32_e32 v10, v8
	v_mov_b32_e32 v11, v8
	v_mov_b32_e32 v12, v8
	v_mov_b32_e32 v13, v8
	v_mov_b32_e32 v14, v8
	v_mov_b32_e32 v15, v8
	v_mov_b32_e32 v24, v8
	v_mov_b32_e32 v25, v8
	v_mov_b32_e32 v26, v8
	v_mov_b32_e32 v27, v8
	v_mov_b32_e32 v28, v8
	v_mov_b32_e32 v29, v8
	v_mov_b32_e32 v30, v8
	v_mov_b32_e32 v31, v8
	v_mov_b32_e32 v40, v8
	v_mov_b32_e32 v41, v8
	v_mov_b32_e32 v42, v8
	v_mov_b32_e32 v43, v8
	v_mov_b32_e32 v44, v8
	v_mov_b32_e32 v45, v8
	v_mov_b32_e32 v46, v8
	v_mov_b32_e32 v47, v8
	v_mov_b32_e32 v56, v8
	v_mov_b32_e32 v57, v8
	v_mov_b32_e32 v58, v8
	v_mov_b32_e32 v59, v8
	v_mov_b32_e32 v60, v8
	v_mov_b32_e32 v61, v8
	v_mov_b32_e32 v62, v8
	v_mov_b32_e32 v63, v8
	v_mov_b32_e32 v16, v8
	v_mov_b32_e32 v17, v8
	v_mov_b32_e32 v18, v8
	v_mov_b32_e32 v19, v8
	v_mov_b32_e32 v20, v8
	v_mov_b32_e32 v21, v8
	v_mov_b32_e32 v22, v8
	v_mov_b32_e32 v23, v8
	v_mov_b32_e32 v32, v8
	v_mov_b32_e32 v33, v8
	v_mov_b32_e32 v34, v8
	v_mov_b32_e32 v35, v8
	v_mov_b32_e32 v36, v8
	v_mov_b32_e32 v37, v8
	v_mov_b32_e32 v38, v8
	v_mov_b32_e32 v39, v8
	v_mov_b32_e32 v48, v8
	v_mov_b32_e32 v49, v8
	v_mov_b32_e32 v50, v8
	v_mov_b32_e32 v51, v8
	v_mov_b32_e32 v52, v8
	v_mov_b32_e32 v53, v8
	v_mov_b32_e32 v54, v8
	v_mov_b32_e32 v55, v8
	v_mov_b32_e32 v64, v8
	v_mov_b32_e32 v65, v8
	v_mov_b32_e32 v66, v8
	v_mov_b32_e32 v67, v8
	v_mov_b32_e32 v68, v8
	v_mov_b32_e32 v69, v8
	v_mov_b32_e32 v70, v8
	v_mov_b32_e32 v71, v8
	v_mov_b32_e32 v72, v8
	v_mov_b32_e32 v73, v8
	v_mov_b32_e32 v74, v8
	v_mov_b32_e32 v75, v8
	v_mov_b32_e32 v76, v8
	v_mov_b32_e32 v77, v8
	v_mov_b32_e32 v78, v8
	v_mov_b32_e32 v79, v8
	v_mov_b32_e32 v88, v8
	v_mov_b32_e32 v89, v8
	v_mov_b32_e32 v90, v8
	v_mov_b32_e32 v91, v8
	v_mov_b32_e32 v92, v8
	v_mov_b32_e32 v93, v8
	v_mov_b32_e32 v94, v8
	v_mov_b32_e32 v95, v8
	v_mov_b32_e32 v104, v8
	v_mov_b32_e32 v105, v8
	v_mov_b32_e32 v106, v8
	v_mov_b32_e32 v107, v8
	v_mov_b32_e32 v108, v8
	v_mov_b32_e32 v109, v8
	v_mov_b32_e32 v110, v8
	v_mov_b32_e32 v111, v8
	v_mov_b32_e32 v120, v8
	v_mov_b32_e32 v121, v8
	v_mov_b32_e32 v122, v8
	v_mov_b32_e32 v123, v8
	v_mov_b32_e32 v124, v8
	v_mov_b32_e32 v125, v8
	v_mov_b32_e32 v126, v8
	v_mov_b32_e32 v127, v8
	v_mov_b32_e32 v80, v8
	v_mov_b32_e32 v81, v8
	v_mov_b32_e32 v82, v8
	v_mov_b32_e32 v83, v8
	v_mov_b32_e32 v84, v8
	v_mov_b32_e32 v85, v8
	v_mov_b32_e32 v86, v8
	v_mov_b32_e32 v87, v8
	v_mov_b32_e32 v96, v8
	v_mov_b32_e32 v97, v8
	v_mov_b32_e32 v98, v8
	v_mov_b32_e32 v99, v8
	v_mov_b32_e32 v100, v8
	v_mov_b32_e32 v101, v8
	v_mov_b32_e32 v102, v8
	v_mov_b32_e32 v103, v8
	v_mov_b32_e32 v112, v8
	v_mov_b32_e32 v113, v8
	v_mov_b32_e32 v114, v8
	v_mov_b32_e32 v115, v8
	v_mov_b32_e32 v116, v8
	v_mov_b32_e32 v117, v8
	v_mov_b32_e32 v118, v8
	v_mov_b32_e32 v119, v8
	v_mov_b32_e32 v128, v8
	v_mov_b32_e32 v129, v8
	v_mov_b32_e32 v130, v8
	v_mov_b32_e32 v131, v8
	v_mov_b32_e32 v132, v8
	v_mov_b32_e32 v133, v8
	v_mov_b32_e32 v134, v8
	v_mov_b32_e32 v135, v8
